# v12_combo
# speedup vs baseline: 1.0149x; 1.0149x over previous
; DI void indexer_item(const Params& p, int b, int qt16, char* smem) {
;     ...
;       const u32 cand = prefix | (1u << bit);
;       int c = 0;
; #pragma unroll
;       for (int rb = 0; rb < 4; ++rb) {
;         if (rb <= nr16) {
; #pragma unroll
;           for (int r = rb * 16; r < rb * 16 + 16; ++r)
;             asm volatile("v_cmp_ge_u32_e32 vcc, %1, %2\n\tv_addc_co_u32_e32 %0, vcc, 0, %0, vcc" : "+v"(c) : "v"(u[r]), "v"(cand) : "vcc");
;         }
;       }
;       c += __builtin_amdgcn_update_dpp(0, c, 0xB1, 0xf, 0xf, true);
;       c += __builtin_amdgcn_update_dpp(0, c, 0x4E, 0xf, 0xf, true);
;       c += __builtin_amdgcn_update_dpp(0, c, 0x141, 0xf, 0xf, true);
;       c += __builtin_amdgcn_update_dpp(0, c, 0x140, 0xf, 0xf, true);
;       const int cnt = __builtin_amdgcn_readlane(c, 0) + __builtin_amdgcn_readlane(c, 16) + __builtin_amdgcn_readlane(c, 32) +
;                       __builtin_amdgcn_readlane(c, 48);
;       if (cnt >= 256) prefix = cand;
;       if (cnt == 256) { exact = true; break; }
.LBB0_446:
	v_add3_u32 v109, v109, v139, v140
	s_nop 1
	v_add_u32_dpp v109, v109, v109 quad_perm:[1,0,3,2] row_mask:0xf bank_mask:0xf bound_ctrl:1
	s_nop 1
	v_add_u32_dpp v109, v109, v109 quad_perm:[2,3,0,1] row_mask:0xf bank_mask:0xf bound_ctrl:1
	s_nop 1
	v_add_u32_dpp v109, v109, v109 row_half_mirror row_mask:0xf bank_mask:0xf bound_ctrl:1
	s_nop 1
	v_add_u32_dpp v109, v109, v109 row_mirror row_mask:0xf bank_mask:0xf bound_ctrl:1
	s_nop 0
	v_readlane_b32 s6, v109, 0
	v_readlane_b32 s7, v109, 16
	s_add_i32 s6, s7, s6
	v_readlane_b32 s7, v109, 32
	s_add_i32 s6, s6, s7
	v_readlane_b32 s7, v109, 48
	s_add_i32 s8, s6, s7
	s_cmpk_gt_i32 s8, 0xff
	s_cselect_b64 vcc, -1, 0
	s_cmpk_lg_i32 s8, 0x100
	s_cselect_b64 s[6:7], -1, 0
	s_cmpk_eq_i32 s8, 0x100
	v_cndmask_b32_e32 v138, v138, v105, vcc
	s_cselect_b64 s[8:9], -1, 0
	v_subrev_co_u32_e32 v108, vcc, 1, v108
	s_or_b64 s[8:9], s[8:9], vcc
	s_andn2_b64 vcc, exec, s[8:9]
	s_cbranch_vccz .LBB0_453
.LBB0_447:
	v_lshlrev_b32_e64 v105, v108, 1
	v_mov_b32_e32 v109, 0
	v_mov_b32_e32 v139, 0
	v_mov_b32_e32 v140, 0
	v_or_b32_e32 v105, v105, v138
	v_cmp_ge_u32_e32 vcc, v3, v105
	v_cmp_ge_u32_e64 s[6:7], v104, v105
	v_cmp_ge_u32_e64 s[8:9], v5, v105
	v_addc_co_u32_e32 v109, vcc, 0, v109, vcc
	v_addc_co_u32_e64 v139, s[6:7], 0, v139, s[6:7]
	v_addc_co_u32_e64 v140, s[8:9], 0, v140, s[8:9]
	v_cmp_ge_u32_e32 vcc, v106, v105
	v_cmp_ge_u32_e64 s[6:7], v41, v105
	v_cmp_ge_u32_e64 s[8:9], v39, v105
	v_addc_co_u32_e32 v109, vcc, 0, v109, vcc
	v_addc_co_u32_e64 v139, s[6:7], 0, v139, s[6:7]
	v_addc_co_u32_e64 v140, s[8:9], 0, v140, s[8:9]
	v_cmp_ge_u32_e32 vcc, v47, v105
	v_cmp_ge_u32_e64 s[6:7], v37, v105
	v_cmp_ge_u32_e64 s[8:9], v45, v105
	v_addc_co_u32_e32 v109, vcc, 0, v109, vcc
	v_addc_co_u32_e64 v139, s[6:7], 0, v139, s[6:7]
	v_addc_co_u32_e64 v140, s[8:9], 0, v140, s[8:9]
	v_cmp_ge_u32_e32 vcc, v43, v105
	v_cmp_ge_u32_e64 s[6:7], v51, v105
	v_cmp_ge_u32_e64 s[8:9], v49, v105
	v_addc_co_u32_e32 v109, vcc, 0, v109, vcc
	v_addc_co_u32_e64 v139, s[6:7], 0, v139, s[6:7]
	v_addc_co_u32_e64 v140, s[8:9], 0, v140, s[8:9]
	v_cmp_ge_u32_e32 vcc, v57, v105
	v_cmp_ge_u32_e64 s[6:7], v55, v105
	v_cmp_ge_u32_e64 s[8:9], v63, v105
	v_addc_co_u32_e32 v109, vcc, 0, v109, vcc
	v_addc_co_u32_e64 v139, s[6:7], 0, v139, s[6:7]
	v_addc_co_u32_e64 v140, s[8:9], 0, v140, s[8:9]
	v_cmp_ge_u32_e32 vcc, v53, v105
	s_nop 1
	v_addc_co_u32_e32 v109, vcc, 0, v109, vcc
	s_andn2_b64 vcc, exec, s[0:1]
	s_cbranch_vccnz .LBB0_450
	v_cmp_ge_u32_e32 vcc, v61, v105
	v_cmp_ge_u32_e64 s[6:7], v59, v105
	v_cmp_ge_u32_e64 s[8:9], v67, v105
	v_addc_co_u32_e32 v109, vcc, 0, v109, vcc
	v_addc_co_u32_e64 v139, s[6:7], 0, v139, s[6:7]
	v_addc_co_u32_e64 v140, s[8:9], 0, v140, s[8:9]
	v_cmp_ge_u32_e32 vcc, v65, v105
	v_cmp_ge_u32_e64 s[6:7], v73, v105
	v_cmp_ge_u32_e64 s[8:9], v71, v105
	v_addc_co_u32_e32 v109, vcc, 0, v109, vcc
	v_addc_co_u32_e64 v139, s[6:7], 0, v139, s[6:7]
	v_addc_co_u32_e64 v140, s[8:9], 0, v140, s[8:9]
	v_cmp_ge_u32_e32 vcc, v79, v105
	v_cmp_ge_u32_e64 s[6:7], v69, v105
	v_cmp_ge_u32_e64 s[8:9], v77, v105
	v_addc_co_u32_e32 v109, vcc, 0, v109, vcc
	v_addc_co_u32_e64 v139, s[6:7], 0, v139, s[6:7]
	v_addc_co_u32_e64 v140, s[8:9], 0, v140, s[8:9]
	v_cmp_ge_u32_e32 vcc, v75, v105
	v_cmp_ge_u32_e64 s[6:7], v83, v105
	v_cmp_ge_u32_e64 s[8:9], v81, v105
	v_addc_co_u32_e32 v109, vcc, 0, v109, vcc
	v_addc_co_u32_e64 v139, s[6:7], 0, v139, s[6:7]
	v_addc_co_u32_e64 v140, s[8:9], 0, v140, s[8:9]
	v_cmp_ge_u32_e32 vcc, v91, v105
	v_cmp_ge_u32_e64 s[6:7], v89, v105
	v_cmp_ge_u32_e64 s[8:9], v97, v105
	v_addc_co_u32_e32 v109, vcc, 0, v109, vcc
	v_addc_co_u32_e64 v139, s[6:7], 0, v139, s[6:7]
	v_addc_co_u32_e64 v140, s[8:9], 0, v140, s[8:9]
	v_cmp_ge_u32_e32 vcc, v85, v105
	s_nop 1
	v_addc_co_u32_e32 v109, vcc, 0, v109, vcc
	s_andn2_b64 vcc, exec, s[2:3]
	s_cbranch_vccz .LBB0_451

; DI void indexer_item(const Params& p, int b, int qt16, char* smem) {
;     ...
;       for (int rb = 0; rb < 4; ++rb) {
;         if (rb <= nr16) {
; #pragma unroll
;           for (int r = rb * 16; r < rb * 16 + 16; ++r)
;             asm volatile("v_cmp_ge_u32_e32 vcc, %1, %2\n\tv_addc_co_u32_e32 %0, vcc, 0, %0, vcc" : "+v"(c) : "v"(u[r]), "v"(cand) : "vcc");
;         }
;       }
.LBB0_451:
	v_cmp_ge_u32_e32 vcc, v95, v105
	v_cmp_ge_u32_e64 s[6:7], v93, v105
	v_cmp_ge_u32_e64 s[8:9], v107, v105
	v_addc_co_u32_e32 v109, vcc, 0, v109, vcc
	v_addc_co_u32_e64 v139, s[6:7], 0, v139, s[6:7]
	v_addc_co_u32_e64 v140, s[8:9], 0, v140, s[8:9]
	v_cmp_ge_u32_e32 vcc, v103, v105
	v_cmp_ge_u32_e64 s[6:7], v112, v105
	v_cmp_ge_u32_e64 s[8:9], v111, v105
	v_addc_co_u32_e32 v109, vcc, 0, v109, vcc
	v_addc_co_u32_e64 v139, s[6:7], 0, v139, s[6:7]
	v_addc_co_u32_e64 v140, s[8:9], 0, v140, s[8:9]
	v_cmp_ge_u32_e32 vcc, v115, v105
	v_cmp_ge_u32_e64 s[6:7], v110, v105
	v_cmp_ge_u32_e64 s[8:9], v114, v105
	v_addc_co_u32_e32 v109, vcc, 0, v109, vcc
	v_addc_co_u32_e64 v139, s[6:7], 0, v139, s[6:7]
	v_addc_co_u32_e64 v140, s[8:9], 0, v140, s[8:9]
	v_cmp_ge_u32_e32 vcc, v113, v105
	v_cmp_ge_u32_e64 s[6:7], v117, v105
	v_cmp_ge_u32_e64 s[8:9], v116, v105
	v_addc_co_u32_e32 v109, vcc, 0, v109, vcc
	v_addc_co_u32_e64 v139, s[6:7], 0, v139, s[6:7]
	v_addc_co_u32_e64 v140, s[8:9], 0, v140, s[8:9]
	v_cmp_ge_u32_e32 vcc, v120, v105
	v_cmp_ge_u32_e64 s[6:7], v119, v105
	v_cmp_ge_u32_e64 s[8:9], v123, v105
	v_addc_co_u32_e32 v109, vcc, 0, v109, vcc
	v_addc_co_u32_e64 v139, s[6:7], 0, v139, s[6:7]
	v_addc_co_u32_e64 v140, s[8:9], 0, v140, s[8:9]
	v_cmp_ge_u32_e32 vcc, v118, v105
	s_nop 1
	v_addc_co_u32_e32 v109, vcc, 0, v109, vcc
	s_andn2_b64 vcc, exec, s[4:5]
	s_cbranch_vccnz .LBB0_446
.LBB0_452:
	v_cmp_ge_u32_e32 vcc, v122, v105
	v_cmp_ge_u32_e64 s[6:7], v121, v105
	v_cmp_ge_u32_e64 s[8:9], v125, v105
	v_addc_co_u32_e32 v109, vcc, 0, v109, vcc
	v_addc_co_u32_e64 v139, s[6:7], 0, v139, s[6:7]
	v_addc_co_u32_e64 v140, s[8:9], 0, v140, s[8:9]
	v_cmp_ge_u32_e32 vcc, v124, v105
	v_cmp_ge_u32_e64 s[6:7], v127, v105
	v_cmp_ge_u32_e64 s[8:9], v126, v105
	v_addc_co_u32_e32 v109, vcc, 0, v109, vcc
	v_addc_co_u32_e64 v139, s[6:7], 0, v139, s[6:7]
	v_addc_co_u32_e64 v140, s[8:9], 0, v140, s[8:9]
	v_cmp_ge_u32_e32 vcc, v129, v105
	v_cmp_ge_u32_e64 s[6:7], v128, v105
	v_cmp_ge_u32_e64 s[8:9], v131, v105
	v_addc_co_u32_e32 v109, vcc, 0, v109, vcc
	v_addc_co_u32_e64 v139, s[6:7], 0, v139, s[6:7]
	v_addc_co_u32_e64 v140, s[8:9], 0, v140, s[8:9]
	v_cmp_ge_u32_e32 vcc, v130, v105
	v_cmp_ge_u32_e64 s[6:7], v133, v105
	v_cmp_ge_u32_e64 s[8:9], v132, v105
	v_addc_co_u32_e32 v109, vcc, 0, v109, vcc
	v_addc_co_u32_e64 v139, s[6:7], 0, v139, s[6:7]
	v_addc_co_u32_e64 v140, s[8:9], 0, v140, s[8:9]
	v_cmp_ge_u32_e32 vcc, v136, v105
	v_cmp_ge_u32_e64 s[6:7], v135, v105
	v_cmp_ge_u32_e64 s[8:9], v137, v105
	v_addc_co_u32_e32 v109, vcc, 0, v109, vcc
	v_addc_co_u32_e64 v139, s[6:7], 0, v139, s[6:7]
	v_addc_co_u32_e64 v140, s[8:9], 0, v140, s[8:9]
	v_cmp_ge_u32_e32 vcc, v134, v105
	s_nop 1
	v_addc_co_u32_e32 v109, vcc, 0, v109, vcc
	s_branch .LBB0_446
